# v56 + phase-1 epilogue output stores write-through and non-temporal (sc1 nt): no dirty lines left for the release at the phase-1 grid barrier, outputs do not displace GEMM operands
# speedup vs baseline: 1.0116x; 1.0116x over previous
.LBB0_191:
	s_cmpk_lt_i32 s92, 0x80
	s_cselect_b64 s[0:1], -1, 0
	s_cmp_gt_i32 s52, 16
	s_cselect_b64 s[4:5], -1, 0
	s_and_b64 s[4:5], s[4:5], s[0:1]
	s_andn2_b64 vcc, exec, s[4:5]
	s_mov_b64 s[4:5], -1
	s_cbranch_vccz .LBB0_209
	s_ashr_i32 s16, s52, 2
	s_cmp_eq_u32 s16, 2
	s_mov_b32 s4, 0xfc00000
	s_cselect_b32 s4, s4, 0x13d00000
	s_cmp_lg_u32 s16, 1
	s_cselect_b32 s4, s4, 0xbb00000
	s_cmp_gt_u32 s52, 3
	s_cselect_b32 s54, s4, 0x7a00000
	s_add_u32 s34, s76, s54
	s_addc_u32 s35, s77, 0
	s_and_b64 s[0:1], s[0:1], exec
	v_readlane_b32 s56, v255, 0
	v_readlane_b32 s63, v255, 7
	v_readlane_b32 s0, v255, 37
	v_readlane_b32 s4, v255, 39
	v_readlane_b32 s5, v255, 41
	v_readlane_b32 s62, v255, 6
	s_cselect_b32 s1, s63, s0
	v_readlane_b32 s0, v255, 36
	s_cselect_b32 s39, s4, s5
	v_readlane_b32 s4, v255, 38
	v_readlane_b32 s5, v255, 40
	s_cselect_b32 s0, s62, s0
	s_cselect_b32 s38, s4, s5
	s_lshl_b32 s55, s92, 8
	s_add_i32 s55, s55, s81
	s_cmp_gt_i32 s52, 16
	s_cselect_b64 s[4:5], -1, 0
	s_cmp_eq_u32 s52, 16
	v_lshl_add_u32 v140, s52, 6, v159
	s_cselect_b64 s[12:13], -1, 0
	s_cmp_lg_u32 s52, 16
	v_lshlrev_b32_e32 v179, 1, v140
	s_cselect_b64 s[10:11], -1, 0
	v_or_b32_e32 v156, s55, v158
	s_mov_b64 s[14:15], -1
	s_and_b64 vcc, exec, s[4:5]
	v_readlane_b32 s57, v255, 1
	v_readlane_b32 s58, v255, 2
	v_readlane_b32 s59, v255, 3
	v_readlane_b32 s60, v255, 4
	v_readlane_b32 s61, v255, 5
	s_cbranch_vccz .LBB0_194
	v_mul_f32_e32 v128, 0xbfb8aa3b, v80
	v_mul_f32_e32 v129, 0xbfb8aa3b, v81
	v_mul_f32_e32 v130, 0xbfb8aa3b, v82
	v_mul_f32_e32 v131, 0xbfb8aa3b, v83
	v_exp_f32_e32 v128, v128
	v_exp_f32_e32 v129, v129
	v_exp_f32_e32 v130, v130
	v_exp_f32_e32 v131, v131
	v_add_f32_e32 v128, 1.0, v128
	v_add_f32_e32 v129, 1.0, v129
	v_add_f32_e32 v130, 1.0, v130
	v_add_f32_e32 v131, 1.0, v131
	v_rcp_f32_e32 v128, v128
	v_rcp_f32_e32 v130, v130
	v_rcp_f32_e32 v131, v131
	v_rcp_f32_e32 v129, v129
	v_pk_mul_f32 v[152:153], v[94:95], v[90:91]
	v_pk_mul_f32 v[154:155], v[92:93], v[88:89]
	v_pk_mul_f32 v[130:131], v[82:83], v[130:131]
	v_pk_mul_f32 v[128:129], v[80:81], v[128:129]
	v_pk_mul_f32 v[130:131], v[86:87], v[130:131]
	v_pk_mul_f32 v[128:129], v[84:85], v[128:129]
	v_lshl_add_u32 v157, v156, 11, v179
	v_cvt_pk_f16_f32 v153, v152, v153
	v_cvt_pk_f16_f32 v152, v154, v155
	v_cvt_pk_f16_f32 v131, v130, v131
	v_cvt_pk_f16_f32 v130, v128, v129
	global_store_dwordx2 v157, v[152:153], s[0:1] sc1 nt
	global_store_dwordx2 v157, v[130:131], s[38:39] sc1 nt
	s_mov_b64 s[14:15], 0
.LBB0_194:
	s_lshl_b32 s17, s52, 8
	v_cndmask_b32_e64 v128, 0, 1, s[10:11]
	s_and_b32 s53, s17, 0x300
	s_andn2_b64 vcc, exec, s[14:15]
	v_cmp_ne_u32_e64 s[10:11], 1, v128
	s_cbranch_vccnz .LBB0_197
	v_lshlrev_b32_e32 v128, 10, v156
	s_and_b64 s[14:15], s[12:13], exec
	v_or3_b32 v128, v128, s53, v142
	s_cselect_b32 s14, 0x17e00000, s54
	v_lshl_or_b32 v129, v156, 8, v160
	v_lshlrev_b32_e32 v128, 1, v128
	s_cselect_b32 s15, 0, 0
	s_add_u32 s14, s76, s14
	v_cvt_pk_f16_f32 v155, v94, v95
	v_cvt_pk_f16_f32 v154, v92, v93
	v_cvt_pk_f16_f32 v153, v86, v87
	v_cvt_pk_f16_f32 v152, v84, v85
	v_cndmask_b32_e64 v129, v128, v129, s[12:13]
	s_addc_u32 s15, s77, s15
	s_and_b64 vcc, exec, s[10:11]
	global_store_dwordx4 v129, v[152:155], s[14:15] sc1 nt
	s_cbranch_vccnz .LBB0_197
	s_nop 0
	v_cvt_pk_f16_f32 v155, v82, v83
	v_cvt_pk_f16_f32 v154, v80, v81
	v_cvt_pk_f16_f32 v153, v90, v91
	v_cvt_pk_f16_f32 v152, v88, v89
	global_store_dwordx4 v128, v[152:155], s[34:35] offset:256 sc1 nt
.LBB0_197:
	v_cndmask_b32_e64 v129, 0, 1, s[4:5]
	v_or_b32_e32 v128, 1, v156
	v_cmp_ne_u32_e64 s[14:15], 1, v129
	s_andn2_b64 vcc, exec, s[4:5]
	s_mov_b64 s[4:5], -1
	s_cbranch_vccnz .LBB0_199
	v_mul_f32_e32 v129, 0xbfb8aa3b, v64
	v_exp_f32_e32 v129, v129
	v_mul_f32_e32 v130, 0xbfb8aa3b, v65
	v_mul_f32_e32 v131, 0xbfb8aa3b, v66
	v_exp_f32_e32 v152, v130
	v_add_f32_e32 v129, 1.0, v129
	v_rcp_f32_e32 v130, v129
	v_exp_f32_e32 v129, v131
	v_mul_f32_e32 v131, 0xbfb8aa3b, v67
	v_exp_f32_e32 v131, v131
	v_add_f32_e32 v154, 1.0, v152
	v_add_f32_e32 v129, 1.0, v129
	v_rcp_f32_e32 v152, v129
	v_add_f32_e32 v129, 1.0, v131
	v_rcp_f32_e32 v153, v129
	v_rcp_f32_e32 v131, v154
	v_pk_mul_f32 v[154:155], v[78:79], v[74:75]
	v_pk_mul_f32 v[180:181], v[76:77], v[72:73]
	v_pk_mul_f32 v[152:153], v[66:67], v[152:153]
	v_pk_mul_f32 v[130:131], v[64:65], v[130:131]
	v_pk_mul_f32 v[152:153], v[70:71], v[152:153]
	v_pk_mul_f32 v[130:131], v[68:69], v[130:131]
	v_lshl_add_u32 v129, v128, 11, v179
	v_cvt_pk_f16_f32 v155, v154, v155
	v_cvt_pk_f16_f32 v154, v180, v181
	v_cvt_pk_f16_f32 v153, v152, v153
	v_cvt_pk_f16_f32 v152, v130, v131
	s_mov_b64 s[4:5], 0
	global_store_dwordx2 v129, v[154:155], s[0:1] sc1 nt
	global_store_dwordx2 v129, v[152:153], s[38:39] sc1 nt
.LBB0_199:
	s_andn2_b64 vcc, exec, s[4:5]
	s_cbranch_vccnz .LBB0_202
	v_lshlrev_b32_e32 v129, 10, v128
	s_and_b64 s[4:5], s[12:13], exec
	v_lshl_or_b32 v130, v128, 8, v160
	v_or3_b32 v128, v129, s53, v142
	s_cselect_b32 s4, 0x17e00000, s54
	v_lshlrev_b32_e32 v128, 1, v128
	s_cselect_b32 s5, 0, 0
	s_add_u32 s4, s76, s4
	v_cvt_pk_f16_f32 v155, v78, v79
	v_cvt_pk_f16_f32 v154, v76, v77
	v_cvt_pk_f16_f32 v153, v70, v71
	v_cvt_pk_f16_f32 v152, v68, v69
	v_cndmask_b32_e64 v129, v128, v130, s[12:13]
	s_addc_u32 s5, s77, s5
	s_and_b64 vcc, exec, s[10:11]
	global_store_dwordx4 v129, v[152:155], s[4:5] sc1 nt
	s_cbranch_vccnz .LBB0_202
	s_nop 0
	v_cvt_pk_f16_f32 v155, v66, v67
	v_cvt_pk_f16_f32 v154, v64, v65
	v_cvt_pk_f16_f32 v153, v74, v75
	v_cvt_pk_f16_f32 v152, v72, v73
	global_store_dwordx4 v128, v[152:155], s[34:35] offset:256 sc1 nt

.LBB0_206:
	v_mul_f32_e32 v128, 0xbfb8aa3b, v48
	v_mul_f32_e32 v129, 0xbfb8aa3b, v49
	v_mul_f32_e32 v130, 0xbfb8aa3b, v50
	v_mul_f32_e32 v131, 0xbfb8aa3b, v51
	v_exp_f32_e32 v128, v128
	v_exp_f32_e32 v129, v129
	v_exp_f32_e32 v130, v130
	v_exp_f32_e32 v131, v131
	v_add_f32_e32 v128, 1.0, v128
	v_add_f32_e32 v129, 1.0, v129
	v_add_f32_e32 v130, 1.0, v130
	v_add_f32_e32 v131, 1.0, v131
	v_rcp_f32_e32 v128, v128
	v_rcp_f32_e32 v130, v130
	v_rcp_f32_e32 v131, v131
	v_rcp_f32_e32 v129, v129
	v_lshl_add_u32 v181, v180, 11, v179
	v_cmp_lt_i32_e32 vcc, -1, v153
	v_pk_mul_f32 v[130:131], v[50:51], v[130:131]
	v_pk_mul_f32 v[128:129], v[48:49], v[128:129]
	v_pk_mul_f32 v[184:185], v[54:55], v[130:131]
	v_pk_mul_f32 v[182:183], v[52:53], v[128:129]
	v_pk_mul_f32 v[130:131], v[126:127], v[122:123]
	v_pk_mul_f32 v[128:129], v[124:125], v[120:121]
	v_cvt_pk_f16_f32 v187, v130, v131
	v_cvt_pk_f16_f32 v186, v128, v129
	v_cvt_pk_f16_f32 v185, v184, v185
	v_cvt_pk_f16_f32 v184, v182, v183
	global_store_dwordx2 v181, v[186:187], s[0:1] sc1 nt
	global_store_dwordx2 v181, v[184:185], s[38:39] sc1 nt
	s_and_saveexec_b64 s[4:5], vcc
	s_cbranch_execz .LBB0_208
	v_readlane_b32 s56, v255, 0
	v_readlane_b32 s62, v255, 6
	v_readlane_b32 s63, v255, 7
	v_ashrrev_i32_e32 v153, 31, v152
	v_lshlrev_b64 v[152:153], 13, v[152:153]
	v_lshl_add_u64 v[154:155], v[154:155], 2, s[62:63]
	v_lshl_add_u64 v[152:153], v[154:155], 0, v[152:153]
	v_lshl_add_u64 v[152:153], v[140:141], 2, v[152:153]
	v_readlane_b32 s57, v255, 1
	v_readlane_b32 s58, v255, 2
	v_readlane_b32 s59, v255, 3
	v_readlane_b32 s60, v255, 4
	v_readlane_b32 s61, v255, 5
	global_store_dwordx4 v[152:153], v[128:131], off sc1 nt

.LBB0_209:
	s_and_b64 vcc, exec, s[4:5]
	s_cbranch_vccz .LBB0_302
	s_lshl_b32 s4, s92, 8
	s_add_i32 s4, s4, s81
	s_and_b32 s0, s4, 0xfc0
	v_or_b32_e32 v128, s0, v158
	s_movk_i32 s0, 0xffc
	v_lshl_add_u32 v140, s52, 6, v159
	v_pk_mul_f32 v[122:123], v[126:127], v[122:123]
	v_pk_mul_f32 v[120:121], v[124:125], v[120:121]
	v_cmp_eq_u32_e32 vcc, s0, v128
	s_and_saveexec_b64 s[0:1], vcc
	s_cbranch_execz .LBB0_212
	s_ashr_i32 s10, s4, 12
	s_ashr_i32 s11, s10, 31
	s_lshl_b64 s[10:11], s[10:11], 13
	v_readlane_b32 s5, v255, 44
	s_add_u32 s10, s5, s10
	v_readlane_b32 s5, v255, 45
	s_addc_u32 s11, s5, s11
	v_lshl_add_u64 v[124:125], v[140:141], 2, s[10:11]
	global_store_dwordx4 v[124:125], v[120:123], off sc1 nt
.LBB0_212:
	s_or_b64 exec, exec, s[0:1]
	s_movk_i32 s0, 0xffa
	v_pk_mul_f32 v[118:119], v[118:119], v[114:115]
	v_pk_mul_f32 v[116:117], v[116:117], v[112:113]
	v_cmp_lt_u32_e32 vcc, s0, v128
	s_and_saveexec_b64 s[0:1], vcc
	s_cbranch_execz .LBB0_214
	s_ashr_i32 s10, s4, 12
	s_ashr_i32 s11, s10, 31
	s_lshl_b64 s[10:11], s[10:11], 13
	v_readlane_b32 s5, v255, 44
	v_add_u32_e32 v112, 0xfffff005, v128
	v_mov_b32_e32 v113, v141
	s_add_u32 s10, s5, s10
	v_readlane_b32 s5, v255, 45
	s_addc_u32 s11, s5, s11
	v_lshlrev_b64 v[112:113], 12, v[112:113]
	v_lshl_add_u64 v[112:113], s[10:11], 0, v[112:113]
	v_lshl_add_u64 v[112:113], v[140:141], 2, v[112:113]
	global_store_dwordx4 v[112:113], v[116:119], off sc1 nt
.LBB0_214:
	s_or_b64 exec, exec, s[0:1]
	s_addk_i32 s4, 0x80
	s_and_b32 s0, s4, 0xfc0
	v_or_b32_e32 v112, s0, v158
	s_movk_i32 s0, 0xffc
	v_pk_mul_f32 v[106:107], v[110:111], v[106:107]
	v_pk_mul_f32 v[104:105], v[108:109], v[104:105]
	v_cmp_eq_u32_e32 vcc, s0, v112
	s_and_saveexec_b64 s[0:1], vcc
	s_cbranch_execz .LBB0_216
	s_ashr_i32 s10, s4, 12
	s_ashr_i32 s11, s10, 31
	s_lshl_b64 s[10:11], s[10:11], 13
	v_readlane_b32 s5, v255, 44
	s_add_u32 s10, s5, s10
	v_readlane_b32 s5, v255, 45
	s_addc_u32 s11, s5, s11
	v_lshl_add_u64 v[108:109], v[140:141], 2, s[10:11]
	global_store_dwordx4 v[108:109], v[104:107], off sc1 nt
.LBB0_216:
	s_or_b64 exec, exec, s[0:1]
	s_movk_i32 s0, 0xffa
	v_pk_mul_f32 v[98:99], v[102:103], v[98:99]
	v_pk_mul_f32 v[96:97], v[100:101], v[96:97]
	v_cmp_lt_u32_e32 vcc, s0, v112
	s_and_saveexec_b64 s[0:1], vcc
	s_cbranch_execz .LBB0_218
	s_ashr_i32 s4, s4, 12
	s_ashr_i32 s5, s4, 31
	s_lshl_b64 s[4:5], s[4:5], 13
	v_readlane_b32 s10, v255, 44
	v_add_u32_e32 v100, 0xfffff005, v112
	v_mov_b32_e32 v101, v141
	s_add_u32 s4, s10, s4
	v_readlane_b32 s10, v255, 45
	s_addc_u32 s5, s10, s5
	v_lshlrev_b64 v[100:101], 12, v[100:101]
	v_lshl_add_u64 v[100:101], s[4:5], 0, v[100:101]
	v_lshl_add_u64 v[100:101], v[140:141], 2, v[100:101]
	global_store_dwordx4 v[100:101], v[96:99], off sc1 nt
.LBB0_218:
	s_or_b64 exec, exec, s[0:1]
	s_mov_b64 s[0:1], exec
	v_readlane_b32 s4, v255, 56
	v_readlane_b32 s5, v255, 57
	s_and_b64 s[4:5], s[0:1], s[4:5]
	s_mov_b64 exec, s[4:5]
	s_cbranch_execz .LBB0_221
	s_and_b64 vcc, exec, s[70:71]
	ds_write_b128 v165, v[120:123]
	ds_write_b128 v165, v[116:119] offset:256
	ds_write_b128 v165, v[104:107] offset:1024
	ds_write_b128 v165, v[96:99] offset:1280
	s_cbranch_vccz .LBB0_221
	s_ashr_i32 s93, s92, 31
	s_lshl_b64 s[4:5], s[92:93], 13
	v_readlane_b32 s10, v255, 46
	s_add_u32 s4, s10, s4
	v_readlane_b32 s10, v255, 47
	s_addc_u32 s5, s10, s5
	v_lshl_add_u64 v[100:101], v[140:141], 2, s[4:5]
	global_store_dwordx4 v[100:101], v[104:107], off sc1 nt
	v_add_co_u32_e32 v100, vcc, 0x1000, v100
	s_nop 1
	v_addc_co_u32_e32 v101, vcc, 0, v101, vcc
	global_store_dwordx4 v[100:101], v[96:99], off sc1 nt

.LBB0_223:
	s_or_b64 exec, exec, s[0:1]
	v_pk_mul_f32 v[90:91], v[94:95], v[90:91]
	v_pk_mul_f32 v[88:89], v[92:93], v[88:89]
	v_mul_f32_e32 v92, 0xbfb8aa3b, v80
	v_mul_f32_e32 v93, 0xbfb8aa3b, v81
	v_mul_f32_e32 v94, 0xbfb8aa3b, v82
	v_mul_f32_e32 v95, 0xbfb8aa3b, v83
	v_exp_f32_e32 v92, v92
	v_exp_f32_e32 v93, v93
	v_exp_f32_e32 v94, v94
	v_exp_f32_e32 v95, v95
	v_add_f32_e32 v92, 1.0, v92
	v_add_f32_e32 v93, 1.0, v93
	v_add_f32_e32 v94, 1.0, v94
	v_add_f32_e32 v95, 1.0, v95
	v_rcp_f32_e32 v92, v92
	v_rcp_f32_e32 v93, v93
	v_rcp_f32_e32 v94, v94
	v_rcp_f32_e32 v95, v95
	s_and_b32 s0, s92, 15
	v_pk_mul_f32 v[80:81], v[80:81], v[92:93]
	s_cmp_lg_u32 s0, 0
	v_pk_mul_f32 v[82:83], v[82:83], v[94:95]
	v_pk_mul_f32 v[80:81], v[84:85], v[80:81]
	v_pk_mul_f32 v[82:83], v[86:87], v[82:83]
	s_waitcnt vmcnt(0) lgkmcnt(0)
	v_pk_mul_f32 v[84:85], v[110:111], v[126:127]
	v_pk_mul_f32 v[86:87], v[108:109], v[124:125]
	v_pk_fma_f32 v[84:85], v[90:91], v[114:115], v[84:85]
	v_pk_fma_f32 v[92:93], v[88:89], v[112:113], v[86:87]
	v_readlane_b32 s4, v255, 62
	s_cselect_b64 s[0:1], -1, 0
	v_pk_fma_f32 v[86:87], v[102:103], v[130:131], v[84:85]
	v_pk_fma_f32 v[84:85], v[100:101], v[128:129], v[92:93]
	v_readlane_b32 s5, v255, 63
	s_and_b64 s[0:1], s[4:5], s[0:1]
	v_pk_mul_f32 v[84:85], v[80:81], v[84:85]
	s_and_saveexec_b64 s[4:5], s[0:1]
	s_xor_b64 s[4:5], exec, s[4:5]
	s_cbranch_execz .LBB0_225
	s_ashr_i32 s93, s92, 31
	s_lshl_b64 s[10:11], s[92:93], 13
	v_readlane_b32 s12, v255, 52
	s_add_u32 s12, s12, s10
	v_readlane_b32 s13, v255, 53
	s_addc_u32 s13, s13, s11
	v_pk_mul_f32 v[86:87], v[82:83], v[86:87]
	v_lshl_add_u64 v[92:93], s[12:13], 0, v[152:153]
	v_readlane_b32 s12, v255, 54
	s_add_u32 s10, s12, s10
	v_readlane_b32 s12, v255, 55
	s_addc_u32 s11, s12, s11
	v_lshl_add_u64 v[94:95], s[10:11], 0, v[152:153]
	global_store_dwordx4 v[92:93], v[84:87], off sc1 nt
	global_store_dwordx4 v[94:95], v[80:83], off sc1 nt
.LBB0_225:
	s_or_saveexec_b64 s[4:5], s[4:5]
	s_nop 0
	v_lshlrev_b32_e32 v80, 1, v140
	s_xor_b64 exec, exec, s[4:5]
	s_cbranch_execz .LBB0_227
	v_pk_mul_f32 v[82:83], v[82:83], v[86:87]
	s_lshl_b32 s10, s92, 19
	v_cvt_pk_f16_f32 v83, v82, v83
	v_cvt_pk_f16_f32 v82, v84, v85
	v_add3_u32 v81, s10, v163, v80
	global_store_dwordx2 v81, v[82:83], s[84:85] sc1 nt
.LBB0_227:
	s_or_b64 exec, exec, s[4:5]
	v_pk_mul_f32 v[74:75], v[78:79], v[74:75]
	v_pk_mul_f32 v[72:73], v[76:77], v[72:73]
	v_mul_f32_e32 v76, 0xbfb8aa3b, v64
	v_mul_f32_e32 v77, 0xbfb8aa3b, v65
	v_mul_f32_e32 v78, 0xbfb8aa3b, v66
	v_mul_f32_e32 v79, 0xbfb8aa3b, v67
	v_exp_f32_e32 v76, v76
	v_exp_f32_e32 v77, v77
	v_exp_f32_e32 v78, v78
	v_exp_f32_e32 v79, v79
	v_add_f32_e32 v76, 1.0, v76
	v_add_f32_e32 v77, 1.0, v77
	v_add_f32_e32 v78, 1.0, v78
	v_add_f32_e32 v79, 1.0, v79
	v_rcp_f32_e32 v76, v76
	v_rcp_f32_e32 v77, v77
	v_rcp_f32_e32 v78, v78
	v_rcp_f32_e32 v79, v79
	v_pk_mul_f32 v[64:65], v[64:65], v[76:77]
	s_nop 0
	v_pk_mul_f32 v[64:65], v[68:69], v[64:65]
	v_pk_mul_f32 v[66:67], v[66:67], v[78:79]
	v_pk_mul_f32 v[68:69], v[74:75], v[114:115]
	v_pk_mul_f32 v[66:67], v[70:71], v[66:67]
	v_pk_mul_f32 v[70:71], v[72:73], v[112:113]
	v_pk_fma_f32 v[68:69], v[90:91], v[110:111], v[68:69]
	v_pk_fma_f32 v[76:77], v[88:89], v[108:109], v[70:71]
	v_pk_fma_f32 v[70:71], v[102:103], v[126:127], v[68:69]
	v_pk_fma_f32 v[68:69], v[100:101], v[124:125], v[76:77]
	s_nop 0
	v_pk_mul_f32 v[68:69], v[64:65], v[68:69]
	s_and_saveexec_b64 s[10:11], s[0:1]
	s_xor_b64 s[0:1], exec, s[10:11]
	s_cbranch_execz .LBB0_229
	s_ashr_i32 s93, s92, 31
	s_lshl_b64 s[4:5], s[92:93], 13
	s_add_u32 s4, s76, s4
	s_addc_u32 s5, s77, s5
	v_lshl_add_u64 v[76:77], v[140:141], 2, s[4:5]
	v_add_co_u32_e32 v78, vcc, 0x1c901000, v76
	v_pk_mul_f32 v[70:71], v[66:67], v[70:71]
	s_nop 0
	v_addc_co_u32_e32 v79, vcc, 0, v77, vcc
	global_store_dwordx4 v[78:79], v[68:71], off sc1 nt
	s_lshl_b32 s4, s92, 19
	s_nop 0
	v_add_co_u32_e32 v68, vcc, 0x1ca01000, v76
	s_nop 1
	v_addc_co_u32_e32 v69, vcc, 0, v77, vcc
	global_store_dwordx4 v[68:69], v[64:67], off sc1 nt
.LBB0_229:
	s_or_saveexec_b64 s[0:1], s[0:1]
	s_nop 0
	v_mov_b32_e32 v64, 0
	v_mov_b32_e32 v65, s4
	s_xor_b64 exec, exec, s[0:1]
	s_cbranch_execz .LBB0_231
	v_pk_mul_f32 v[64:65], v[66:67], v[70:71]
	s_lshl_b32 s4, s92, 19
	v_cvt_pk_f16_f32 v65, v64, v65
	v_cvt_pk_f16_f32 v64, v68, v69
	v_add3_u32 v66, v164, s4, v80
	global_store_dwordx2 v66, v[64:65], s[84:85] sc1 nt
	v_mov_b32_e32 v65, s4
	v_mov_b32_e32 v64, v163
.LBB0_231:
	s_or_b64 exec, exec, s[0:1]
	v_mul_f32_e32 v66, 0xbfb8aa3b, v56
	v_mul_f32_e32 v67, 0xbfb8aa3b, v57
	v_mul_f32_e32 v68, 0xbfb8aa3b, v58
	v_mul_f32_e32 v69, 0xbfb8aa3b, v59
	v_exp_f32_e32 v66, v66
	v_exp_f32_e32 v67, v67
	v_exp_f32_e32 v68, v68
	v_exp_f32_e32 v69, v69
	v_add_f32_e32 v66, 1.0, v66
	v_add_f32_e32 v67, 1.0, v67
	v_add_f32_e32 v68, 1.0, v68
	v_add_f32_e32 v69, 1.0, v69
	v_rcp_f32_e32 v66, v66
	v_rcp_f32_e32 v67, v67
	v_rcp_f32_e32 v68, v68
	v_rcp_f32_e32 v69, v69
	v_pk_mul_f32 v[56:57], v[56:57], v[66:67]
	s_nop 0
	v_pk_mul_f32 v[60:61], v[60:61], v[56:57]
	v_pk_mul_f32 v[58:59], v[58:59], v[68:69]
	v_mul_f32_e32 v56, 0xbfb8aa3b, v48
	v_pk_mul_f32 v[58:59], v[62:63], v[58:59]
	v_mul_f32_e32 v57, 0xbfb8aa3b, v49
	v_mul_f32_e32 v62, 0xbfb8aa3b, v50
	v_mul_f32_e32 v63, 0xbfb8aa3b, v51
	v_exp_f32_e32 v56, v56
	v_exp_f32_e32 v57, v57
	v_exp_f32_e32 v62, v62
	v_exp_f32_e32 v63, v63
	v_add_f32_e32 v56, 1.0, v56
	v_add_f32_e32 v57, 1.0, v57
	v_add_f32_e32 v62, 1.0, v62
	v_add_f32_e32 v63, 1.0, v63
	v_rcp_f32_e32 v56, v56
	v_rcp_f32_e32 v57, v57
	v_rcp_f32_e32 v62, v62
	v_rcp_f32_e32 v63, v63
	v_pk_mul_f32 v[48:49], v[48:49], v[56:57]
	s_nop 0
	v_pk_mul_f32 v[48:49], v[52:53], v[48:49]
	v_pk_mul_f32 v[50:51], v[50:51], v[62:63]
	v_pk_mul_f32 v[52:53], v[122:123], v[114:115]
	v_pk_mul_f32 v[50:51], v[54:55], v[50:51]
	v_pk_mul_f32 v[54:55], v[120:121], v[112:113]
	v_pk_fma_f32 v[52:53], v[74:75], v[110:111], v[52:53]
	v_pk_fma_f32 v[54:55], v[72:73], v[108:109], v[54:55]
	v_pk_fma_f32 v[52:53], v[90:91], v[102:103], v[52:53]
	v_pk_fma_f32 v[54:55], v[88:89], v[100:101], v[54:55]
	v_pk_mul_f32 v[50:51], v[50:51], v[52:53]
	v_pk_mul_f32 v[48:49], v[48:49], v[54:55]
	v_cvt_pk_f16_f32 v51, v50, v51
	v_cvt_pk_f16_f32 v50, v48, v49
	v_add_u32_e32 v48, v65, v64
	v_add_u32_e32 v56, v80, v48
	v_add_u32_e32 v48, 0x1000, v56
	global_store_dwordx2 v48, v[50:51], s[84:85] sc1 nt
	v_pk_mul_f32 v[48:49], v[118:119], v[114:115]
	v_pk_mul_f32 v[50:51], v[116:117], v[112:113]
	v_pk_fma_f32 v[48:49], v[122:123], v[110:111], v[48:49]
	v_pk_fma_f32 v[50:51], v[120:121], v[108:109], v[50:51]
	v_pk_fma_f32 v[48:49], v[74:75], v[102:103], v[48:49]
	v_pk_fma_f32 v[50:51], v[72:73], v[100:101], v[50:51]
	v_pk_mul_f32 v[48:49], v[58:59], v[48:49]
	v_pk_mul_f32 v[50:51], v[60:61], v[50:51]
	v_cvt_pk_f16_f32 v49, v48, v49
	v_cvt_pk_f16_f32 v48, v50, v51
	v_add_u32_e32 v50, 0x1800, v56
	global_store_dwordx2 v50, v[48:49], s[84:85] sc1 nt
	v_mov_b32_dpp v48, v96 row_shr:1 row_mask:0xf bank_mask:0xf bound_ctrl:1
	v_mov_b32_dpp v52, v104 row_shr:1 row_mask:0xf bank_mask:0xf bound_ctrl:1
	v_mov_b32_dpp v49, v97 row_shr:1 row_mask:0xf bank_mask:0xf bound_ctrl:1
	v_mov_b32_dpp v53, v105 row_shr:1 row_mask:0xf bank_mask:0xf bound_ctrl:1
	v_mov_b32_dpp v50, v98 row_shr:1 row_mask:0xf bank_mask:0xf bound_ctrl:1
	v_mov_b32_dpp v54, v106 row_shr:1 row_mask:0xf bank_mask:0xf bound_ctrl:1
	v_mov_b32_dpp v51, v99 row_shr:1 row_mask:0xf bank_mask:0xf bound_ctrl:1
	v_mov_b32_dpp v55, v107 row_shr:1 row_mask:0xf bank_mask:0xf bound_ctrl:1
	s_mov_b64 s[0:1], exec
	v_readlane_b32 s4, v255, 58
	v_readlane_b32 s5, v255, 59
	s_and_b64 s[4:5], s[0:1], s[4:5]
	s_mov_b64 exec, s[4:5]
	s_cbranch_execz .LBB0_233
	ds_read_b128 v[52:55], v165 offset:512
	ds_read_b128 v[48:51], v165 offset:768
.LBB0_233:
	s_or_b64 exec, exec, s[0:1]
	v_pk_mul_f32 v[26:27], v[34:35], v[26:27]
	v_pk_mul_f32 v[24:25], v[32:33], v[24:25]
	v_mul_f32_e32 v32, 0xbfb8aa3b, v16
	v_mul_f32_e32 v33, 0xbfb8aa3b, v17
	v_mul_f32_e32 v34, 0xbfb8aa3b, v18
	v_mul_f32_e32 v35, 0xbfb8aa3b, v19
	v_exp_f32_e32 v32, v32
	v_exp_f32_e32 v33, v33
	v_exp_f32_e32 v34, v34
	v_exp_f32_e32 v35, v35
	v_pk_mul_f32 v[42:43], v[46:47], v[42:43]
	v_pk_mul_f32 v[40:41], v[44:45], v[40:41]
	v_mul_f32_e32 v44, 0xbfb8aa3b, v28
	v_mul_f32_e32 v45, 0xbfb8aa3b, v29
	v_mul_f32_e32 v46, 0xbfb8aa3b, v30
	v_mul_f32_e32 v47, 0xbfb8aa3b, v31
	v_exp_f32_e32 v44, v44
	v_exp_f32_e32 v45, v45
	v_exp_f32_e32 v46, v46
	v_exp_f32_e32 v47, v47
	v_add_f32_e32 v32, 1.0, v32
	v_add_f32_e32 v33, 1.0, v33
	v_add_f32_e32 v34, 1.0, v34
	v_add_f32_e32 v35, 1.0, v35
	v_rcp_f32_e32 v32, v32
	v_rcp_f32_e32 v33, v33
	v_rcp_f32_e32 v34, v34
	v_rcp_f32_e32 v35, v35
	v_add_f32_e32 v44, 1.0, v44
	v_add_f32_e32 v45, 1.0, v45
	v_add_f32_e32 v46, 1.0, v46
	v_add_f32_e32 v47, 1.0, v47
	v_rcp_f32_e32 v44, v44
	v_rcp_f32_e32 v45, v45
	v_rcp_f32_e32 v46, v46
	v_rcp_f32_e32 v47, v47
	v_pk_mul_f32 v[16:17], v[16:17], v[32:33]
	v_pk_mul_f32 v[18:19], v[18:19], v[34:35]
	v_pk_mul_f32 v[16:17], v[20:21], v[16:17]
	v_pk_mul_f32 v[18:19], v[22:23], v[18:19]
	s_waitcnt lgkmcnt(0)
	v_pk_mul_f32 v[20:21], v[110:111], v[50:51]
	v_pk_mul_f32 v[22:23], v[108:109], v[48:49]
	v_pk_mul_f32 v[28:29], v[28:29], v[44:45]
	v_pk_mul_f32 v[30:31], v[30:31], v[46:47]
	v_pk_fma_f32 v[20:21], v[42:43], v[114:115], v[20:21]
	v_pk_fma_f32 v[22:23], v[40:41], v[112:113], v[22:23]
	v_pk_mul_f32 v[30:31], v[38:39], v[30:31]
	v_pk_mul_f32 v[28:29], v[36:37], v[28:29]
	v_pk_fma_f32 v[20:21], v[102:103], v[54:55], v[20:21]
	v_pk_fma_f32 v[22:23], v[100:101], v[52:53], v[22:23]
	v_pk_mul_f32 v[20:21], v[30:31], v[20:21]
	v_pk_mul_f32 v[22:23], v[28:29], v[22:23]
	v_cvt_pk_f16_f32 v21, v20, v21
	v_cvt_pk_f16_f32 v20, v22, v23
	v_add_u32_e32 v22, 0x40000, v56
	global_store_dwordx2 v22, v[20:21], s[84:85] sc1 nt
	v_pk_mul_f32 v[20:21], v[26:27], v[114:115]
	v_pk_mul_f32 v[22:23], v[24:25], v[112:113]
	v_pk_fma_f32 v[20:21], v[42:43], v[110:111], v[20:21]
	v_pk_fma_f32 v[22:23], v[40:41], v[108:109], v[22:23]
	v_pk_fma_f32 v[20:21], v[102:103], v[50:51], v[20:21]
	v_pk_fma_f32 v[22:23], v[100:101], v[48:49], v[22:23]
	v_pk_mul_f32 v[18:19], v[18:19], v[20:21]
	v_pk_mul_f32 v[16:17], v[16:17], v[22:23]
	v_cvt_pk_f16_f32 v19, v18, v19
	v_cvt_pk_f16_f32 v18, v16, v17
	v_add_u32_e32 v16, 0x40800, v56
	global_store_dwordx2 v16, v[18:19], s[84:85] sc1 nt
	v_mul_f32_e32 v16, 0xbfb8aa3b, v8
	v_mul_f32_e32 v17, 0xbfb8aa3b, v9
	v_mul_f32_e32 v18, 0xbfb8aa3b, v10
	v_mul_f32_e32 v19, 0xbfb8aa3b, v11
	v_exp_f32_e32 v16, v16
	v_exp_f32_e32 v17, v17
	v_exp_f32_e32 v18, v18
	v_exp_f32_e32 v19, v19
	v_add_f32_e32 v16, 1.0, v16
	v_add_f32_e32 v17, 1.0, v17
	v_add_f32_e32 v18, 1.0, v18
	v_add_f32_e32 v19, 1.0, v19
	v_rcp_f32_e32 v16, v16
	v_rcp_f32_e32 v17, v17
	v_rcp_f32_e32 v18, v18
	v_rcp_f32_e32 v19, v19
	v_pk_mul_f32 v[8:9], v[8:9], v[16:17]
	s_nop 0
	v_pk_mul_f32 v[8:9], v[12:13], v[8:9]
	v_pk_mul_f32 v[10:11], v[10:11], v[18:19]
	v_mul_f32_e32 v12, 0xbfb8aa3b, v0
	v_pk_mul_f32 v[10:11], v[14:15], v[10:11]
	v_mul_f32_e32 v13, 0xbfb8aa3b, v1
	v_mul_f32_e32 v14, 0xbfb8aa3b, v2
	v_mul_f32_e32 v15, 0xbfb8aa3b, v3
	v_exp_f32_e32 v12, v12
	v_exp_f32_e32 v13, v13
	v_exp_f32_e32 v14, v14
	v_exp_f32_e32 v15, v15
	v_add_f32_e32 v12, 1.0, v12
	v_add_f32_e32 v13, 1.0, v13
	v_add_f32_e32 v14, 1.0, v14
	v_add_f32_e32 v15, 1.0, v15
	v_rcp_f32_e32 v12, v12
	v_rcp_f32_e32 v13, v13
	v_rcp_f32_e32 v14, v14
	v_rcp_f32_e32 v15, v15
	v_pk_mul_f32 v[0:1], v[0:1], v[12:13]
	s_nop 0
	v_pk_mul_f32 v[0:1], v[4:5], v[0:1]
	v_pk_mul_f32 v[2:3], v[2:3], v[14:15]
	v_pk_mul_f32 v[4:5], v[106:107], v[114:115]
	v_pk_mul_f32 v[2:3], v[6:7], v[2:3]
	v_pk_mul_f32 v[6:7], v[104:105], v[112:113]
	v_pk_fma_f32 v[4:5], v[26:27], v[110:111], v[4:5]
	v_pk_fma_f32 v[6:7], v[24:25], v[108:109], v[6:7]
	v_pk_fma_f32 v[4:5], v[42:43], v[102:103], v[4:5]
	v_pk_fma_f32 v[6:7], v[40:41], v[100:101], v[6:7]
	v_pk_mul_f32 v[2:3], v[2:3], v[4:5]
	v_pk_mul_f32 v[0:1], v[0:1], v[6:7]
	v_cvt_pk_f16_f32 v3, v2, v3
	v_cvt_pk_f16_f32 v2, v0, v1
	v_add_u32_e32 v0, 0x41000, v56
	global_store_dwordx2 v0, v[2:3], s[84:85] sc1 nt
	v_pk_mul_f32 v[0:1], v[98:99], v[114:115]
	v_pk_mul_f32 v[2:3], v[96:97], v[112:113]
	v_pk_fma_f32 v[0:1], v[106:107], v[110:111], v[0:1]
	v_pk_fma_f32 v[2:3], v[104:105], v[108:109], v[2:3]
	v_pk_fma_f32 v[0:1], v[26:27], v[102:103], v[0:1]
	v_pk_fma_f32 v[2:3], v[24:25], v[100:101], v[2:3]
	v_pk_mul_f32 v[0:1], v[10:11], v[0:1]
	v_pk_mul_f32 v[2:3], v[8:9], v[2:3]
	v_cvt_pk_f16_f32 v1, v0, v1
	v_cvt_pk_f16_f32 v0, v2, v3
	v_add_u32_e32 v2, 0x41800, v56
	global_store_dwordx2 v2, v[0:1], s[84:85] sc1 nt
	s_andn2_b64 vcc, exec, s[8:9]
	s_mov_b64 s[0:1], -1
	s_cbranch_vccnz .LBB0_180
	s_branch .LBB0_303

.LBB0_237:
	v_lshlrev_b32_e32 v128, 10, v180
	s_and_b64 s[4:5], s[12:13], exec
	v_or3_b32 v128, v128, s53, v142
	s_cselect_b32 s4, 0x17e00000, s54
	v_lshl_or_b32 v129, v180, 8, v160
	v_lshlrev_b32_e32 v128, 1, v128
	s_cselect_b32 s5, 0, 0
	s_add_u32 s4, s76, s4
	v_cvt_pk_f16_f32 v155, v126, v127
	v_cvt_pk_f16_f32 v154, v124, v125
	v_cvt_pk_f16_f32 v153, v54, v55
	v_cvt_pk_f16_f32 v152, v52, v53
	v_cndmask_b32_e64 v129, v128, v129, s[12:13]
	s_addc_u32 s5, s77, s5
	s_and_b64 vcc, exec, s[10:11]
	global_store_dwordx4 v129, v[152:155], s[4:5] sc1 nt
	s_cbranch_vccnz .LBB0_239
	s_nop 0
	v_cvt_pk_f16_f32 v155, v50, v51
	v_cvt_pk_f16_f32 v154, v48, v49
	v_cvt_pk_f16_f32 v153, v122, v123
	v_cvt_pk_f16_f32 v152, v120, v121
	global_store_dwordx4 v128, v[152:155], s[34:35] offset:256 sc1 nt

.LBB0_244:
	s_or_b64 exec, exec, s[4:5]
	s_lshl_b32 s4, s16, 10
	s_cmp_lg_u32 s16, 3
	s_cselect_b32 s16, s4, 0xc80
	s_and_b64 vcc, exec, s[14:15]
	s_mov_b64 s[4:5], -1
	s_cbranch_vccnz .LBB0_248
	v_mul_f32_e32 v128, 0xbfb8aa3b, v56
	v_mul_f32_e32 v129, 0xbfb8aa3b, v57
	v_mul_f32_e32 v130, 0xbfb8aa3b, v58
	v_mul_f32_e32 v131, 0xbfb8aa3b, v59
	v_exp_f32_e32 v128, v128
	v_exp_f32_e32 v129, v129
	v_exp_f32_e32 v130, v130
	v_exp_f32_e32 v131, v131
	v_add_f32_e32 v128, 1.0, v128
	v_add_f32_e32 v129, 1.0, v129
	v_add_f32_e32 v130, 1.0, v130
	v_add_f32_e32 v131, 1.0, v131
	v_rcp_f32_e32 v128, v128
	v_rcp_f32_e32 v130, v130
	v_rcp_f32_e32 v131, v131
	v_rcp_f32_e32 v129, v129
	v_lshl_add_u32 v153, v180, 11, v179
	v_cmp_lt_i32_e32 vcc, -1, v154
	v_pk_mul_f32 v[130:131], v[58:59], v[130:131]
	v_pk_mul_f32 v[128:129], v[56:57], v[128:129]
	v_pk_mul_f32 v[182:183], v[62:63], v[130:131]
	v_pk_mul_f32 v[156:157], v[60:61], v[128:129]
	v_pk_mul_f32 v[130:131], v[118:119], v[114:115]
	v_pk_mul_f32 v[128:129], v[116:117], v[112:113]
	v_cvt_pk_f16_f32 v185, v130, v131
	v_cvt_pk_f16_f32 v184, v128, v129
	v_cvt_pk_f16_f32 v183, v182, v183
	v_cvt_pk_f16_f32 v182, v156, v157
	global_store_dwordx2 v153, v[184:185], s[0:1] sc1 nt
	global_store_dwordx2 v153, v[182:183], s[38:39] sc1 nt
	s_and_saveexec_b64 s[4:5], vcc
	s_cbranch_execz .LBB0_247
	v_readlane_b32 s56, v255, 0
	v_cndmask_b32_e64 v156, v175, v176, s[86:87]
	v_mov_b32_e32 v157, v141
	v_readlane_b32 s62, v255, 6
	v_readlane_b32 s63, v255, 7
	v_ashrrev_i32_e32 v153, 31, v152
	v_mov_b32_e32 v155, v141
	v_lshl_add_u64 v[156:157], s[62:63], 0, v[156:157]
	v_lshlrev_b64 v[182:183], 13, v[152:153]
	v_lshl_add_u64 v[156:157], v[156:157], 0, v[182:183]
	v_lshlrev_b64 v[182:183], 12, v[154:155]
	v_lshl_add_u64 v[156:157], v[156:157], 0, v[182:183]
	v_lshl_add_u64 v[156:157], v[140:141], 2, v[156:157]
	v_readlane_b32 s57, v255, 1
	v_readlane_b32 s58, v255, 2
	v_readlane_b32 s59, v255, 3
	v_readlane_b32 s60, v255, 4
	v_readlane_b32 s61, v255, 5
	global_store_dwordx4 v[156:157], v[128:131], off sc1 nt

.LBB0_248:
	s_andn2_b64 vcc, exec, s[4:5]
	s_or_b32 s4, s16, s53
	s_cbranch_vccnz .LBB0_259
	v_lshl_or_b32 v153, v180, 10, s53
	v_cvt_pk_f16_f32 v131, v118, v119
	v_cvt_pk_f16_f32 v130, v116, v117
	v_cvt_pk_f16_f32 v129, v62, v63
	v_cvt_pk_f16_f32 v128, v60, v61
	s_and_b64 vcc, exec, s[10:11]
	s_mov_b64 s[16:17], -1
	s_cbranch_vccnz .LBB0_251
	v_or_b32_e32 v155, v153, v142
	v_lshlrev_b32_e32 v155, 1, v155
	v_or_b32_e32 v156, s4, v142
	s_mov_b64 s[16:17], 0
	global_store_dwordx4 v155, v[128:131], s[34:35] sc1 nt
.LBB0_251:
	s_andn2_b64 vcc, exec, s[16:17]
	s_cbranch_vccnz .LBB0_253
	v_readlane_b32 s16, v255, 42
	v_lshl_or_b32 v155, v180, 8, v160
	v_readlane_b32 s17, v255, 43
	v_mov_b32_e32 v156, v161
	s_nop 3
	global_store_dwordx4 v155, v[128:131], s[16:17] sc1 nt
.LBB0_253:
	s_movk_i32 s5, 0x4200
	v_cmp_eq_u32_e64 s[16:17], 1, v154
	v_cndmask_b32_e64 v130, v177, v178, s[86:87]
	v_mad_i64_i32 v[128:129], s[56:57], v152, s5, 0
	s_and_saveexec_b64 s[86:87], s[16:17]
	s_cbranch_execz .LBB0_255
	v_readlane_b32 s56, v255, 0
	v_lshlrev_b32_e32 v154, 2, v130
	v_mov_b32_e32 v155, v141
	v_readlane_b32 s62, v255, 6
	v_readlane_b32 s63, v255, 7
	v_ashrrev_i32_e32 v157, 31, v156
	v_readlane_b32 s57, v255, 1
	v_lshl_add_u64 v[154:155], s[62:63], 0, v[154:155]
	v_lshl_add_u64 v[154:155], v[154:155], 0, v[128:129]
	v_lshl_add_u64 v[154:155], v[156:157], 2, v[154:155]
	v_readlane_b32 s58, v255, 2
	v_readlane_b32 s59, v255, 3
	v_readlane_b32 s60, v255, 4
	v_readlane_b32 s61, v255, 5
	global_store_dwordx4 v[154:155], v[60:63], off sc1 nt
	global_store_dwordx4 v[154:155], v[116:119], off offset:16 sc1 nt
.LBB0_255:
	s_or_b64 exec, exec, s[86:87]
	s_and_b64 vcc, exec, s[10:11]
	s_cbranch_vccnz .LBB0_259
	v_or_b32_e32 v131, v153, v162
	v_cvt_pk_f16_f32 v157, v58, v59
	v_cvt_pk_f16_f32 v156, v56, v57
	v_cvt_pk_f16_f32 v155, v114, v115
	v_cvt_pk_f16_f32 v154, v112, v113
	v_lshlrev_b32_e32 v131, 1, v131
	global_store_dwordx4 v131, v[154:157], s[34:35] sc1 nt
	s_and_saveexec_b64 s[86:87], s[16:17]
	s_cbranch_execz .LBB0_258
	v_readlane_b32 s56, v255, 0
	v_lshlrev_b32_e32 v130, 2, v130
	v_mov_b32_e32 v131, v141
	v_readlane_b32 s62, v255, 6
	v_readlane_b32 s63, v255, 7
	s_ashr_i32 s5, s4, 31
	v_readlane_b32 s57, v255, 1
	v_lshl_add_u64 v[130:131], s[62:63], 0, v[130:131]
	v_lshl_add_u64 v[128:129], v[130:131], 0, v[128:129]
	v_lshl_add_u64 v[130:131], s[4:5], 0, v[142:143]
	v_lshl_add_u64 v[128:129], v[130:131], 2, v[128:129]
	v_readlane_b32 s58, v255, 2
	v_readlane_b32 s59, v255, 3
	v_readlane_b32 s60, v255, 4
	v_readlane_b32 s61, v255, 5
	global_store_dwordx4 v[128:129], v[112:115], off offset:512 sc1 nt
	global_store_dwordx4 v[128:129], v[56:59], off offset:528 sc1 nt

.LBB0_259:
	s_addk_i32 s55, 0x80
	v_or_b32_e32 v156, s55, v158
	s_and_b64 vcc, exec, s[14:15]
	s_mov_b64 s[16:17], -1
	s_cbranch_vccnz .LBB0_261
	v_mul_f32_e32 v128, 0xbfb8aa3b, v28
	v_mul_f32_e32 v129, 0xbfb8aa3b, v29
	v_mul_f32_e32 v130, 0xbfb8aa3b, v30
	v_mul_f32_e32 v131, 0xbfb8aa3b, v31
	v_exp_f32_e32 v128, v128
	v_exp_f32_e32 v129, v129
	v_exp_f32_e32 v130, v130
	v_exp_f32_e32 v131, v131
	v_add_f32_e32 v128, 1.0, v128
	v_add_f32_e32 v129, 1.0, v129
	v_add_f32_e32 v130, 1.0, v130
	v_add_f32_e32 v131, 1.0, v131
	v_rcp_f32_e32 v128, v128
	v_rcp_f32_e32 v130, v130
	v_rcp_f32_e32 v131, v131
	v_rcp_f32_e32 v129, v129
	v_pk_mul_f32 v[152:153], v[46:47], v[42:43]
	v_pk_mul_f32 v[154:155], v[44:45], v[40:41]
	v_pk_mul_f32 v[130:131], v[30:31], v[130:131]
	v_pk_mul_f32 v[128:129], v[28:29], v[128:129]
	v_pk_mul_f32 v[130:131], v[38:39], v[130:131]
	v_pk_mul_f32 v[128:129], v[36:37], v[128:129]
	v_lshl_add_u32 v157, v156, 11, v179
	v_cvt_pk_f16_f32 v153, v152, v153
	v_cvt_pk_f16_f32 v152, v154, v155
	v_cvt_pk_f16_f32 v131, v130, v131
	v_cvt_pk_f16_f32 v130, v128, v129
	s_mov_b64 s[16:17], 0
	global_store_dwordx2 v157, v[152:153], s[0:1] sc1 nt
	global_store_dwordx2 v157, v[130:131], s[38:39] sc1 nt
.LBB0_261:
	s_andn2_b64 vcc, exec, s[16:17]
	s_movk_i32 s86, 0x7fff
	s_cbranch_vccnz .LBB0_264
	v_lshlrev_b32_e32 v128, 10, v156
	s_and_b64 s[16:17], s[12:13], exec
	v_or3_b32 v128, v128, s53, v142
	s_cselect_b32 s16, 0x17e00000, s54
	v_lshl_or_b32 v129, v156, 8, v160
	v_lshlrev_b32_e32 v128, 1, v128
	s_cselect_b32 s5, 0, 0
	s_add_u32 s16, s76, s16
	v_cvt_pk_f16_f32 v155, v46, v47
	v_cvt_pk_f16_f32 v154, v44, v45
	v_cvt_pk_f16_f32 v153, v38, v39
	v_cvt_pk_f16_f32 v152, v36, v37
	v_cndmask_b32_e64 v129, v128, v129, s[12:13]
	s_addc_u32 s17, s77, s5
	s_and_b64 vcc, exec, s[10:11]
	global_store_dwordx4 v129, v[152:155], s[16:17] sc1 nt
	s_cbranch_vccnz .LBB0_264
	s_nop 0
	v_cvt_pk_f16_f32 v155, v30, v31
	v_cvt_pk_f16_f32 v154, v28, v29
	v_cvt_pk_f16_f32 v153, v42, v43
	v_cvt_pk_f16_f32 v152, v40, v41
	global_store_dwordx4 v128, v[152:155], s[34:35] offset:256 sc1 nt
.LBB0_264:
	v_or_b32_e32 v128, 1, v156
	s_and_b64 vcc, exec, s[14:15]
	s_mov_b64 s[16:17], -1
	s_cbranch_vccnz .LBB0_266
	v_mul_f32_e32 v129, 0xbfb8aa3b, v16
	v_exp_f32_e32 v129, v129
	v_mul_f32_e32 v130, 0xbfb8aa3b, v17
	v_mul_f32_e32 v131, 0xbfb8aa3b, v18
	v_exp_f32_e32 v152, v130
	v_add_f32_e32 v129, 1.0, v129
	v_rcp_f32_e32 v130, v129
	v_exp_f32_e32 v129, v131
	v_mul_f32_e32 v131, 0xbfb8aa3b, v19
	v_exp_f32_e32 v131, v131
	v_add_f32_e32 v154, 1.0, v152
	v_add_f32_e32 v129, 1.0, v129
	v_rcp_f32_e32 v152, v129
	v_add_f32_e32 v129, 1.0, v131
	v_rcp_f32_e32 v153, v129
	v_rcp_f32_e32 v131, v154
	v_pk_mul_f32 v[154:155], v[34:35], v[26:27]
	v_pk_mul_f32 v[180:181], v[32:33], v[24:25]
	v_pk_mul_f32 v[152:153], v[18:19], v[152:153]
	v_pk_mul_f32 v[130:131], v[16:17], v[130:131]
	v_pk_mul_f32 v[152:153], v[22:23], v[152:153]
	v_pk_mul_f32 v[130:131], v[20:21], v[130:131]
	v_lshl_add_u32 v129, v128, 11, v179
	v_cvt_pk_f16_f32 v155, v154, v155
	v_cvt_pk_f16_f32 v154, v180, v181
	v_cvt_pk_f16_f32 v153, v152, v153
	v_cvt_pk_f16_f32 v152, v130, v131
	s_mov_b64 s[16:17], 0
	global_store_dwordx2 v129, v[154:155], s[0:1] sc1 nt
	global_store_dwordx2 v129, v[152:153], s[38:39] sc1 nt
.LBB0_266:
	s_andn2_b64 vcc, exec, s[16:17]
	s_cbranch_vccnz .LBB0_269
	v_lshlrev_b32_e32 v129, 10, v128
	s_and_b64 s[16:17], s[12:13], exec
	v_lshl_or_b32 v130, v128, 8, v160
	v_or3_b32 v128, v129, s53, v142
	s_cselect_b32 s16, 0x17e00000, s54
	v_lshlrev_b32_e32 v128, 1, v128
	s_cselect_b32 s5, 0, 0
	s_add_u32 s16, s76, s16
	v_cvt_pk_f16_f32 v155, v34, v35
	v_cvt_pk_f16_f32 v154, v32, v33
	v_cvt_pk_f16_f32 v153, v22, v23
	v_cvt_pk_f16_f32 v152, v20, v21
	v_cndmask_b32_e64 v129, v128, v130, s[12:13]
	s_addc_u32 s17, s77, s5
	s_and_b64 vcc, exec, s[10:11]
	global_store_dwordx4 v129, v[152:155], s[16:17] sc1 nt
	s_cbranch_vccnz .LBB0_269
	s_nop 0
	v_cvt_pk_f16_f32 v155, v18, v19
	v_cvt_pk_f16_f32 v154, v16, v17
	v_cvt_pk_f16_f32 v153, v26, v27
	v_cvt_pk_f16_f32 v152, v24, v25
	global_store_dwordx4 v128, v[152:155], s[34:35] offset:256 sc1 nt

.LBB0_273:
	v_mul_f32_e32 v128, 0xbfb8aa3b, v0
	v_mul_f32_e32 v129, 0xbfb8aa3b, v1
	v_mul_f32_e32 v130, 0xbfb8aa3b, v2
	v_mul_f32_e32 v131, 0xbfb8aa3b, v3
	v_exp_f32_e32 v128, v128
	v_exp_f32_e32 v129, v129
	v_exp_f32_e32 v130, v130
	v_exp_f32_e32 v131, v131
	v_add_f32_e32 v128, 1.0, v128
	v_add_f32_e32 v129, 1.0, v129
	v_add_f32_e32 v130, 1.0, v130
	v_add_f32_e32 v131, 1.0, v131
	v_rcp_f32_e32 v128, v128
	v_rcp_f32_e32 v130, v130
	v_rcp_f32_e32 v131, v131
	v_rcp_f32_e32 v129, v129
	v_lshl_add_u32 v181, v180, 11, v179
	v_cmp_lt_i32_e32 vcc, -1, v153
	v_pk_mul_f32 v[130:131], v[2:3], v[130:131]
	v_pk_mul_f32 v[128:129], v[0:1], v[128:129]
	v_pk_mul_f32 v[184:185], v[6:7], v[130:131]
	v_pk_mul_f32 v[182:183], v[4:5], v[128:129]
	v_pk_mul_f32 v[130:131], v[110:111], v[106:107]
	v_pk_mul_f32 v[128:129], v[108:109], v[104:105]
	v_cvt_pk_f16_f32 v187, v130, v131
	v_cvt_pk_f16_f32 v186, v128, v129
	v_cvt_pk_f16_f32 v185, v184, v185
	v_cvt_pk_f16_f32 v184, v182, v183
	global_store_dwordx2 v181, v[186:187], s[0:1] sc1 nt
	global_store_dwordx2 v181, v[184:185], s[38:39] sc1 nt
	s_and_saveexec_b64 s[16:17], vcc
	s_cbranch_execz .LBB0_275
	v_readlane_b32 s56, v255, 0
	v_readlane_b32 s62, v255, 6
	v_readlane_b32 s63, v255, 7
	v_ashrrev_i32_e32 v153, 31, v152
	v_lshlrev_b64 v[152:153], 13, v[152:153]
	v_lshl_add_u64 v[154:155], v[154:155], 2, s[62:63]
	v_lshl_add_u64 v[152:153], v[154:155], 0, v[152:153]
	v_lshl_add_u64 v[152:153], v[140:141], 2, v[152:153]
	v_readlane_b32 s57, v255, 1
	v_readlane_b32 s58, v255, 2
	v_readlane_b32 s59, v255, 3
	v_readlane_b32 s60, v255, 4
	v_readlane_b32 s61, v255, 5
	global_store_dwordx4 v[152:153], v[128:131], off sc1 nt

.LBB0_279:
	v_lshlrev_b32_e32 v128, 10, v180
	v_or3_b32 v128, v128, s53, v142
	v_lshl_or_b32 v129, v180, 8, v160
	v_lshlrev_b32_e32 v128, 1, v128
	v_cndmask_b32_e64 v129, v128, v129, s[12:13]
	s_and_b64 s[12:13], s[12:13], exec
	s_cselect_b32 s12, 0x17e00000, s54
	s_cselect_b32 s13, 0, 0
	s_add_u32 s12, s76, s12
	v_cvt_pk_f16_f32 v155, v110, v111
	v_cvt_pk_f16_f32 v154, v108, v109
	v_cvt_pk_f16_f32 v153, v6, v7
	v_cvt_pk_f16_f32 v152, v4, v5
	s_addc_u32 s13, s77, s13
	s_and_b64 vcc, exec, s[10:11]
	global_store_dwordx4 v129, v[152:155], s[12:13] sc1 nt
	s_cbranch_vccnz .LBB0_281
	s_nop 0
	v_cvt_pk_f16_f32 v155, v2, v3
	v_cvt_pk_f16_f32 v154, v0, v1
	v_cvt_pk_f16_f32 v153, v106, v107
	v_cvt_pk_f16_f32 v152, v104, v105
	global_store_dwordx4 v128, v[152:155], s[34:35] offset:256 sc1 nt

.LBB0_285:
	v_mul_f32_e32 v128, 0xbfb8aa3b, v8
	v_mul_f32_e32 v129, 0xbfb8aa3b, v9
	v_mul_f32_e32 v130, 0xbfb8aa3b, v10
	v_mul_f32_e32 v131, 0xbfb8aa3b, v11
	v_exp_f32_e32 v128, v128
	v_exp_f32_e32 v129, v129
	v_exp_f32_e32 v130, v130
	v_exp_f32_e32 v131, v131
	v_add_f32_e32 v128, 1.0, v128
	v_add_f32_e32 v129, 1.0, v129
	v_add_f32_e32 v130, 1.0, v130
	v_add_f32_e32 v131, 1.0, v131
	v_rcp_f32_e32 v128, v128
	v_rcp_f32_e32 v130, v130
	v_rcp_f32_e32 v131, v131
	v_rcp_f32_e32 v129, v129
	v_lshl_add_u32 v153, v180, 11, v179
	v_cmp_lt_i32_e32 vcc, -1, v154
	v_pk_mul_f32 v[130:131], v[10:11], v[130:131]
	v_pk_mul_f32 v[128:129], v[8:9], v[128:129]
	v_pk_mul_f32 v[182:183], v[14:15], v[130:131]
	v_pk_mul_f32 v[156:157], v[12:13], v[128:129]
	v_pk_mul_f32 v[130:131], v[102:103], v[98:99]
	v_pk_mul_f32 v[128:129], v[100:101], v[96:97]
	v_cvt_pk_f16_f32 v185, v130, v131
	v_cvt_pk_f16_f32 v184, v128, v129
	v_cvt_pk_f16_f32 v183, v182, v183
	v_cvt_pk_f16_f32 v182, v156, v157
	global_store_dwordx2 v153, v[184:185], s[0:1] sc1 nt
	global_store_dwordx2 v153, v[182:183], s[38:39] sc1 nt
	s_and_saveexec_b64 s[0:1], vcc
	s_cbranch_execz .LBB0_287
	v_readlane_b32 s56, v255, 0
	v_cndmask_b32_e64 v156, v175, v176, s[16:17]
	v_mov_b32_e32 v157, v141
	v_readlane_b32 s62, v255, 6
	v_readlane_b32 s63, v255, 7
	v_ashrrev_i32_e32 v153, 31, v152
	v_mov_b32_e32 v155, v141
	v_lshl_add_u64 v[156:157], s[62:63], 0, v[156:157]
	v_lshlrev_b64 v[182:183], 13, v[152:153]
	v_lshl_add_u64 v[156:157], v[156:157], 0, v[182:183]
	v_lshlrev_b64 v[182:183], 12, v[154:155]
	v_lshl_add_u64 v[156:157], v[156:157], 0, v[182:183]
	v_lshl_add_u64 v[156:157], v[140:141], 2, v[156:157]
	v_readlane_b32 s57, v255, 1
	v_readlane_b32 s58, v255, 2
	v_readlane_b32 s59, v255, 3
	v_readlane_b32 s60, v255, 4
	v_readlane_b32 s61, v255, 5
	global_store_dwordx4 v[156:157], v[128:131], off sc1 nt

.LBB0_291:
	v_lshl_or_b32 v153, v180, 10, s53
	v_cvt_pk_f16_f32 v131, v102, v103
	v_cvt_pk_f16_f32 v130, v100, v101
	v_cvt_pk_f16_f32 v129, v14, v15
	v_cvt_pk_f16_f32 v128, v12, v13
	s_and_b64 vcc, exec, s[10:11]
	s_mov_b64 s[0:1], -1
	s_cbranch_vccnz .LBB0_293
	v_or_b32_e32 v140, v153, v142
	v_lshlrev_b32_e32 v140, 1, v140
	v_or_b32_e32 v156, s4, v142
	s_mov_b64 s[0:1], 0
	global_store_dwordx4 v140, v[128:131], s[34:35] sc1 nt
.LBB0_293:
	s_andn2_b64 vcc, exec, s[0:1]
	s_cbranch_vccnz .LBB0_295
	v_readlane_b32 s0, v255, 42
	v_lshl_or_b32 v140, v180, 8, v160
	v_readlane_b32 s1, v255, 43
	v_mov_b32_e32 v156, v161
	s_nop 3
	global_store_dwordx4 v140, v[128:131], s[0:1] sc1 nt
.LBB0_295:
	s_movk_i32 s0, 0x4200
	v_cmp_eq_u32_e64 s[12:13], 1, v154
	v_cndmask_b32_e64 v130, v177, v178, s[16:17]
	v_mad_i64_i32 v[128:129], s[0:1], v152, s0, 0
	s_and_saveexec_b64 s[0:1], s[12:13]
	s_cbranch_execz .LBB0_297
	v_readlane_b32 s56, v255, 0
	v_lshlrev_b32_e32 v140, 2, v130
	v_readlane_b32 s62, v255, 6
	v_readlane_b32 s63, v255, 7
	v_ashrrev_i32_e32 v157, 31, v156
	v_readlane_b32 s57, v255, 1
	v_lshl_add_u64 v[154:155], s[62:63], 0, v[140:141]
	v_lshl_add_u64 v[154:155], v[154:155], 0, v[128:129]
	v_lshl_add_u64 v[154:155], v[156:157], 2, v[154:155]
	v_readlane_b32 s58, v255, 2
	v_readlane_b32 s59, v255, 3
	v_readlane_b32 s60, v255, 4
	v_readlane_b32 s61, v255, 5
	global_store_dwordx4 v[154:155], v[12:15], off sc1 nt
	global_store_dwordx4 v[154:155], v[100:103], off offset:16 sc1 nt
.LBB0_297:
	s_or_b64 exec, exec, s[0:1]
	s_and_b64 vcc, exec, s[10:11]
	s_cbranch_vccnz .LBB0_301
	v_or_b32_e32 v131, v153, v162
	v_cvt_pk_f16_f32 v157, v10, v11
	v_cvt_pk_f16_f32 v156, v8, v9
	v_cvt_pk_f16_f32 v155, v98, v99
	v_cvt_pk_f16_f32 v154, v96, v97
	v_lshlrev_b32_e32 v131, 1, v131
	global_store_dwordx4 v131, v[154:157], s[34:35] sc1 nt
	s_and_saveexec_b64 s[0:1], s[12:13]
	s_cbranch_execz .LBB0_300
	v_readlane_b32 s56, v255, 0
	v_lshlrev_b32_e32 v140, 2, v130
	v_readlane_b32 s62, v255, 6
	v_readlane_b32 s63, v255, 7
	s_ashr_i32 s5, s4, 31
	v_readlane_b32 s57, v255, 1
	v_lshl_add_u64 v[130:131], s[62:63], 0, v[140:141]
	v_lshl_add_u64 v[128:129], v[130:131], 0, v[128:129]
	v_lshl_add_u64 v[130:131], s[4:5], 0, v[142:143]
	v_lshl_add_u64 v[128:129], v[130:131], 2, v[128:129]
	v_readlane_b32 s58, v255, 2
	v_readlane_b32 s59, v255, 3
	v_readlane_b32 s60, v255, 4
	v_readlane_b32 s61, v255, 5
	global_store_dwordx4 v[128:129], v[96:99], off offset:512 sc1 nt
	global_store_dwordx4 v[128:129], v[8:11], off offset:528 sc1 nt
